# start-time stagger for the out-projection and score GEMM phases (group (blockIdx>>3)&3 sleeps 2 resp. 1 x s_sleep 127 per group step) so epilogue HBM bursts overlap other groups' K-loops
# baseline (speedup 1.0000x reference)
.LBB0_565:
	s_or_b64 exec, exec, s[0:1]
	s_cmpk_lt_i32 s2, 0x400
	s_cselect_b64 s[0:1], -1, 0
	v_readfirstlane_b32 s17, v200
	s_and_b64 vcc, exec, s[0:1]
	s_waitcnt lgkmcnt(0)
	s_barrier
	s_lshr_b32 s98, s2, 3
	s_and_b32 s98, s98, 3
	s_mul_i32 s98, s98, 2
	s_cmp_eq_u32 s98, 0
	s_cbranch_scc1 .Lstg3_done
.Lstg3_loop:
	s_sleep 127
	s_sub_u32 s98, s98, 1
	s_cmp_lg_u32 s98, 0
	s_cbranch_scc1 .Lstg3_loop
.Lstg3_done:
	s_cbranch_vccz .LBB0_567
	s_lshr_b32 s6, s16, 22
	s_add_i32 s6, s2, s6
	s_and_b32 s6, s6, 0xfc00
	s_sub_i32 s6, s2, s6
	s_sext_i32_i16 s7, s6
	s_bfe_u32 s7, s7, 0x3001c
	s_add_i32 s7, s6, s7
	s_sext_i32_i16 s12, s7
	s_and_b32 s7, s7, 0xfff8
	s_sub_i32 s6, s6, s7
	s_ashr_i32 s12, s12, 3
	s_mul_i32 s7, s6, 0x81
	s_lshl_b32 s13, s6, 7
	s_sext_i32_i16 s6, s6
	s_cmp_lt_i32 s6, 0
	s_cselect_b32 s6, s7, s13
	s_add_i32 s6, s6, s12
	s_sext_i32_i16 s7, s6
	s_bfe_u32 s7, s7, 0x5001a
	s_add_i32 s7, s6, s7
	s_sext_i32_i16 s12, s7
	s_and_b32 s7, s7, 0xffe0
	s_sub_i32 s6, s6, s7
	s_bfe_i32 s7, s6, 0x80000
	s_bfe_u32 s7, s7, 0x3000c
	s_add_i32 s7, s6, s7
	s_bfe_i32 s13, s7, 0x80000
	s_and_b32 s7, s7, 0xf8
	s_ashr_i32 s12, s12, 5
	s_sub_i32 s6, s6, s7
	s_lshl_b32 s12, s12, 3
	s_sext_i32_i16 s13, s13
	s_sext_i32_i8 s6, s6
	s_add_i32 s56, s12, s6
	s_ashr_i32 s54, s13, 3

.LBB0_656:
	s_or_b64 exec, exec, s[0:1]
	s_lshr_b32 s0, s16, 21
	s_add_i32 s0, s2, s0
	s_and_b32 s0, s0, 0xf800
	s_sub_i32 s0, s2, s0
	s_sext_i32_i16 s1, s0
	s_bfe_u32 s1, s1, 0x3001c
	s_add_i32 s1, s0, s1
	s_sext_i32_i16 s4, s1
	s_and_b32 s1, s1, 0xfff8
	s_sub_i32 s6, s0, s1
	s_lshr_b32 s17, s4, 3
	s_sext_i32_i16 s0, s6
	s_cmp_lt_i32 s0, 0
	s_cselect_b64 s[10:11], -1, 0
	s_cmp_gt_i32 s0, -1
	s_cselect_b64 s[0:1], -1, 0
	s_cmpk_lt_i32 s2, 0x800
	s_cselect_b64 s[4:5], -1, 0
	s_mul_i32 s30, s6, 0x101
	s_and_b64 vcc, exec, s[4:5]
	s_waitcnt lgkmcnt(0)
	s_barrier
	s_lshr_b32 s98, s2, 3
	s_and_b32 s98, s98, 3
	s_mul_i32 s98, s98, 1
	s_cmp_eq_u32 s98, 0
	s_cbranch_scc1 .Lstg4_done

.Lstg4_done:
	s_cbranch_vccz .LBB0_660
	s_andn2_b64 vcc, exec, s[0:1]
	s_mov_b32 s0, s30
	s_cbranch_vccnz .LBB0_659
	s_lshl_b32 s0, s6, 8

	.amdhsa_kernel _Z4mega6Params
		.amdhsa_group_segment_fixed_size 0
		.amdhsa_private_segment_fixed_size 0
		.amdhsa_kernarg_size 416
		.amdhsa_user_sgpr_count 2
		.amdhsa_user_sgpr_dispatch_ptr 0
		.amdhsa_user_sgpr_queue_ptr 0
		.amdhsa_user_sgpr_kernarg_segment_ptr 1
		.amdhsa_user_sgpr_dispatch_id 0
		.amdhsa_user_sgpr_kernarg_preload_length 0
		.amdhsa_user_sgpr_kernarg_preload_offset 0
		.amdhsa_user_sgpr_private_segment_size 0
		.amdhsa_uses_dynamic_stack 0
		.amdhsa_enable_private_segment 0
		.amdhsa_system_sgpr_workgroup_id_x 1
		.amdhsa_system_sgpr_workgroup_id_y 0
		.amdhsa_system_sgpr_workgroup_id_z 0
		.amdhsa_system_sgpr_workgroup_info 0
		.amdhsa_system_vgpr_workitem_id 2
		.amdhsa_next_free_vgpr 256
		.amdhsa_next_free_sgpr 99
		.amdhsa_accum_offset 256
		.amdhsa_reserve_vcc 1
		.amdhsa_float_round_mode_32 0
		.amdhsa_float_round_mode_16_64 0
		.amdhsa_float_denorm_mode_32 3
		.amdhsa_float_denorm_mode_16_64 3
		.amdhsa_dx10_clamp 1
		.amdhsa_ieee_mode 1
		.amdhsa_fp16_overflow 0
		.amdhsa_tg_split 0
		.amdhsa_exception_fp_ieee_invalid_op 0
		.amdhsa_exception_fp_denorm_src 0
		.amdhsa_exception_fp_ieee_div_zero 0
		.amdhsa_exception_fp_ieee_overflow 0
		.amdhsa_exception_fp_ieee_underflow 0
		.amdhsa_exception_fp_ieee_inexact 0
		.amdhsa_exception_int_div_zero 0
	.end_amdhsa_kernel

amdhsa.kernels:
  - .agpr_count:     0
    .args:
      - .offset:         0
        .size:           160
        .value_kind:     by_value
      - .offset:         160
        .size:           4
        .value_kind:     hidden_block_count_x
      - .offset:         164
        .size:           4
        .value_kind:     hidden_block_count_y
      - .offset:         168
        .size:           4
        .value_kind:     hidden_block_count_z
      - .offset:         172
        .size:           2
        .value_kind:     hidden_group_size_x
      - .offset:         174
        .size:           2
        .value_kind:     hidden_group_size_y
      - .offset:         176
        .size:           2
        .value_kind:     hidden_group_size_z
      - .offset:         178
        .size:           2
        .value_kind:     hidden_remainder_x
      - .offset:         180
        .size:           2
        .value_kind:     hidden_remainder_y
      - .offset:         182
        .size:           2
        .value_kind:     hidden_remainder_z
      - .offset:         200
        .size:           8
        .value_kind:     hidden_global_offset_x
      - .offset:         208
        .size:           8
        .value_kind:     hidden_global_offset_y
      - .offset:         216
        .size:           8
        .value_kind:     hidden_global_offset_z
      - .offset:         224
        .size:           2
        .value_kind:     hidden_grid_dims
      - .offset:         248
        .size:           8
        .value_kind:     hidden_multigrid_sync_arg
      - .offset:         280
        .size:           4
        .value_kind:     hidden_dynamic_lds_size
    .group_segment_fixed_size: 0
    .kernarg_segment_align: 8
    .kernarg_segment_size: 416
    .language:       OpenCL C
    .language_version:
      - 2
      - 0
    .max_flat_workgroup_size: 512
    .name:           _Z4mega6Params
    .private_segment_fixed_size: 0
    .sgpr_count:     105
    .sgpr_spill_count: 62
    .symbol:         _Z4mega6Params.kd
    .uniform_work_group_size: 1
    .uses_dynamic_stack: false
    .vgpr_count:     256
    .vgpr_spill_count: 0
    .wavefront_size: 64
